# grid barrier census (first barrier): the 16 per-XCC counter loads issued together instead of one round trip each
# speedup vs baseline: 1.0063x; 1.0008x over previous
.LBB0_639:
	v_mov_b64_e32 v[30:31], s[4:5]
	v_mov_b64_e32 v[32:33], s[6:7]
	flat_load_dword v1, v[30:31] offset:1024 sc1
	flat_load_dword v0, v[30:31] offset:1280 sc1
	flat_load_dword v2, v[30:31] offset:1536 sc1
	flat_load_dword v3, v[30:31] offset:1792 sc1
	flat_load_dword v4, v[30:31] offset:2048 sc1
	flat_load_dword v5, v[30:31] offset:2304 sc1
	flat_load_dword v6, v[30:31] offset:2560 sc1
	flat_load_dword v7, v[30:31] offset:2816 sc1
	flat_load_dword v8, v[30:31] offset:3072 sc1
	flat_load_dword v9, v[30:31] offset:3328 sc1
	flat_load_dword v10, v[30:31] offset:3584 sc1
	flat_load_dword v11, v[30:31] offset:3840 sc1
	flat_load_dword v12, v[32:33] sc1
	flat_load_dword v13, v[32:33] offset:256 sc1
	flat_load_dword v14, v[32:33] offset:512 sc1
	flat_load_dword v15, v[32:33] offset:768 sc1
	s_or_b64 s[50:51], s[50:51], exec
	s_or_b64 s[48:49], s[48:49], exec
	s_waitcnt vmcnt(0) lgkmcnt(0)
	v_add3_u32 v16, v0, v1, v2
	v_add3_u32 v16, v16, v3, v4
	v_add3_u32 v16, v16, v5, v6
	v_add3_u32 v16, v16, v7, v8
	v_add3_u32 v16, v16, v9, v10
	v_add3_u32 v16, v16, v11, v12
	v_add3_u32 v16, v16, v13, v14
	v_add_u32_e32 v16, v16, v15
	v_cmp_ne_u32_e32 vcc, s65, v16
	s_and_saveexec_b64 s[52:53], vcc
	s_cbranch_execz .LBB0_638
	s_and_b32 s56, s66, 0xff
	s_mov_b64 s[54:55], -1
	s_cmp_eq_u32 s56, 0
	s_mov_b64 s[58:59], -1
	s_mov_b64 s[56:57], -1
	s_sleep 1
	s_cbranch_scc1 .LBB0_642
	s_and_saveexec_b64 s[60:61], s[58:59]
	s_cbranch_execz .LBB0_637
	s_branch .LBB0_645
